# W_o residual epilogue: x - mean with packed f32 adds (8 instead of 16 per row group)
# baseline (speedup 1.0000x reference)
;     DI void operator()(Acc& acc, const Unit& u, int wr, int wc, int fr, int fq) const {
;     ...
;             for (int bj = 0; bj < 2; ++bj) {
;                 f32x4 gv0 = *(const f32x4*)(g + EPI_COL8(bj)), gv1 = *(const f32x4*)(g + EPI_COL8(bj) + 4);
;                 f32x4 c0 = {0.f, 0.f, 0.f, 0.f}, c1 = {0.f, 0.f, 0.f, 0.f};
;                 if (ln) { c0 = *(const f32x4*)(lb + col0 + EPI_COL8(bj)) * ALPHA; c1 = *(const f32x4*)(lb + col0 + EPI_COL8(bj) + 4) * ALPHA; }
; #pragma unroll
;                 for (int ai = 0; ai < 2; ++ai)
; #pragma unroll
;                     for (int m = 0; m < 4; ++m) { acc[ai][bj][m][0] = acc[ai][bj][m][0] * gv0 + c0; acc[ai][bj][m][1] = acc[ai][bj][m][1] * gv1 + c1; }
;             }
;     ...
;         const float* xib = (from_input ? xin_ptr(F, row0) : xrow_ptr(F, row0)) + col0; float* xob = xrow_ptr(F, row0) + col0;
;         int oz_ = 0; asm volatile("" : "+v"(oz_));
; #pragma unroll
;         for (int aim = 0; aim < 8; ++aim) { const int ai = aim >> 2, m = aim & 3;
;             f32x4 xa[2][2]; f32x2 sv = {0.f, 1.f};
;             if (ln) sv = *(const f32x2*)(st + 2 * (size_t)(row0 + EPI_ROWS(ai, m) + oz_));
; #pragma unroll
;             for (int bj = 0; bj < 2; ++bj) { const float* p = xib + (size_t)(EPI_ROWS(ai, m) + oz_) * D + EPI_COL8(bj); xa[bj][0] = *(const f32x4*)p; xa[bj][1] = *(const f32x4*)(p + 4); }
; #pragma unroll
;             for (int bj = 0; bj < 2; ++bj) { float* p = xob + (size_t)(EPI_ROWS(ai, m) + oz_) * D + EPI_COL8(bj);
;                 *(f32x4*)p = ((xa[bj][0] - sv[0]) * sv[1]) * la[bj][0] + acc[ai][bj][m][0];
;                 *(f32x4*)(p + 4) = ((xa[bj][1] - sv[0]) * sv[1]) * la[bj][1] + acc[ai][bj][m][1]; }
.Lres_o_fold:
	v_pk_fma_f32 v[134:135], v[134:135], v[64:65], v[158:159]
	v_pk_fma_f32 v[136:137], v[136:137], v[66:67], v[160:161]
	v_pk_fma_f32 v[118:119], v[118:119], v[64:65], v[158:159]
	v_pk_fma_f32 v[120:121], v[120:121], v[66:67], v[160:161]
	v_pk_fma_f32 v[102:103], v[102:103], v[64:65], v[158:159]
	v_pk_fma_f32 v[104:105], v[104:105], v[66:67], v[160:161]
	v_pk_fma_f32 v[84:85], v[84:85], v[64:65], v[158:159]
	v_pk_fma_f32 v[86:87], v[86:87], v[66:67], v[160:161]
	v_pk_fma_f32 v[52:53], v[52:53], v[64:65], v[158:159]
	v_pk_fma_f32 v[54:55], v[54:55], v[66:67], v[160:161]
	v_pk_fma_f32 v[36:37], v[36:37], v[64:65], v[158:159]
	v_pk_fma_f32 v[38:39], v[38:39], v[66:67], v[160:161]
	v_pk_fma_f32 v[20:21], v[20:21], v[64:65], v[158:159]
	v_pk_fma_f32 v[22:23], v[22:23], v[66:67], v[160:161]
	v_pk_fma_f32 v[8:9], v[8:9], v[64:65], v[158:159]
	v_pk_fma_f32 v[10:11], v[10:11], v[66:67], v[160:161]
	v_pk_fma_f32 v[130:131], v[130:131], v[68:69], v[162:163]
	v_pk_fma_f32 v[132:133], v[132:133], v[70:71], v[164:165]
	v_pk_fma_f32 v[114:115], v[114:115], v[68:69], v[162:163]
	v_pk_fma_f32 v[116:117], v[116:117], v[70:71], v[164:165]
	v_pk_fma_f32 v[98:99], v[98:99], v[68:69], v[162:163]
	v_pk_fma_f32 v[100:101], v[100:101], v[70:71], v[164:165]
	v_pk_fma_f32 v[80:81], v[80:81], v[68:69], v[162:163]
	v_pk_fma_f32 v[82:83], v[82:83], v[70:71], v[164:165]
	v_pk_fma_f32 v[48:49], v[48:49], v[68:69], v[162:163]
	v_pk_fma_f32 v[50:51], v[50:51], v[70:71], v[164:165]
	v_pk_fma_f32 v[32:33], v[32:33], v[68:69], v[162:163]
	v_pk_fma_f32 v[34:35], v[34:35], v[70:71], v[164:165]
	v_pk_fma_f32 v[16:17], v[16:17], v[68:69], v[162:163]
	v_pk_fma_f32 v[18:19], v[18:19], v[70:71], v[164:165]
	v_pk_fma_f32 v[4:5], v[4:5], v[68:69], v[162:163]
	v_pk_fma_f32 v[6:7], v[6:7], v[70:71], v[164:165]
	v_pk_fma_f32 v[142:143], v[142:143], v[72:73], v[166:167]
	v_pk_fma_f32 v[144:145], v[144:145], v[74:75], v[168:169]
	v_pk_fma_f32 v[126:127], v[126:127], v[72:73], v[166:167]
	v_pk_fma_f32 v[128:129], v[128:129], v[74:75], v[168:169]
	v_pk_fma_f32 v[110:111], v[110:111], v[72:73], v[166:167]
	v_pk_fma_f32 v[112:113], v[112:113], v[74:75], v[168:169]
	v_pk_fma_f32 v[92:93], v[92:93], v[72:73], v[166:167]
	v_pk_fma_f32 v[94:95], v[94:95], v[74:75], v[168:169]
	v_pk_fma_f32 v[60:61], v[60:61], v[72:73], v[166:167]
	v_pk_fma_f32 v[62:63], v[62:63], v[74:75], v[168:169]
	v_pk_fma_f32 v[44:45], v[44:45], v[72:73], v[166:167]
	v_pk_fma_f32 v[46:47], v[46:47], v[74:75], v[168:169]
	v_pk_fma_f32 v[28:29], v[28:29], v[72:73], v[166:167]
	v_pk_fma_f32 v[30:31], v[30:31], v[74:75], v[168:169]
	v_pk_fma_f32 v[12:13], v[12:13], v[72:73], v[166:167]
	v_pk_fma_f32 v[14:15], v[14:15], v[74:75], v[168:169]
	v_pk_fma_f32 v[138:139], v[138:139], v[76:77], v[170:171]
	v_pk_fma_f32 v[140:141], v[140:141], v[78:79], v[172:173]
	v_pk_fma_f32 v[122:123], v[122:123], v[76:77], v[170:171]
	v_pk_fma_f32 v[124:125], v[124:125], v[78:79], v[172:173]
	v_pk_fma_f32 v[106:107], v[106:107], v[76:77], v[170:171]
	v_pk_fma_f32 v[108:109], v[108:109], v[78:79], v[172:173]
	v_pk_fma_f32 v[88:89], v[88:89], v[76:77], v[170:171]
	v_pk_fma_f32 v[90:91], v[90:91], v[78:79], v[172:173]
	v_pk_fma_f32 v[56:57], v[56:57], v[76:77], v[170:171]
	v_pk_fma_f32 v[58:59], v[58:59], v[78:79], v[172:173]
	v_pk_fma_f32 v[40:41], v[40:41], v[76:77], v[170:171]
	v_pk_fma_f32 v[42:43], v[42:43], v[78:79], v[172:173]
	v_pk_fma_f32 v[24:25], v[24:25], v[76:77], v[170:171]
	v_pk_fma_f32 v[26:27], v[26:27], v[78:79], v[172:173]
	v_pk_fma_f32 v[0:1], v[0:1], v[76:77], v[170:171]
	v_pk_fma_f32 v[2:3], v[2:3], v[78:79], v[172:173]
	s_add_u32 s40, s10, 0x10000
	s_addc_u32 s41, s11, 0
	global_load_dwordx4 v[64:67], v206, s[40:41]
	global_load_dwordx4 v[68:71], v206, s[40:41] offset:16
	global_load_dwordx4 v[72:75], v206, s[40:41] offset:512
	global_load_dwordx4 v[76:79], v206, s[40:41] offset:528
	s_add_u32 s40, s10, 0x20000
	s_addc_u32 s41, s11, 0
	global_load_dwordx4 v[158:161], v206, s[40:41]
	global_load_dwordx4 v[162:165], v206, s[40:41] offset:16
	global_load_dwordx4 v[166:169], v206, s[40:41] offset:512
	global_load_dwordx4 v[170:173], v206, s[40:41] offset:528
	s_mov_b64 s[12:13], s[34:35]
	s_waitcnt vmcnt(8)
	v_pk_add_f32 v[188:189], v[188:189], v[244:245] op_sel_hi:[1,0] neg_lo:[0,1] neg_hi:[0,1]
	v_pk_add_f32 v[190:191], v[190:191], v[244:245] op_sel_hi:[1,0] neg_lo:[0,1] neg_hi:[0,1]
	v_pk_add_f32 v[192:193], v[192:193], v[244:245] op_sel_hi:[1,0] neg_lo:[0,1] neg_hi:[0,1]
	v_pk_add_f32 v[194:195], v[194:195], v[244:245] op_sel_hi:[1,0] neg_lo:[0,1] neg_hi:[0,1]
	v_pk_add_f32 v[196:197], v[196:197], v[244:245] op_sel_hi:[1,0] neg_lo:[0,1] neg_hi:[0,1]
	v_pk_add_f32 v[198:199], v[198:199], v[244:245] op_sel_hi:[1,0] neg_lo:[0,1] neg_hi:[0,1]
	v_pk_add_f32 v[200:201], v[200:201], v[244:245] op_sel_hi:[1,0] neg_lo:[0,1] neg_hi:[0,1]
	v_pk_add_f32 v[202:203], v[202:203], v[244:245] op_sel_hi:[1,0] neg_lo:[0,1] neg_hi:[0,1]
	v_pk_mul_f32 v[188:189], v[244:245], v[188:189] op_sel:[1,0]
	v_pk_mul_f32 v[190:191], v[244:245], v[190:191] op_sel:[1,0]
	v_pk_mul_f32 v[192:193], v[244:245], v[192:193] op_sel:[1,0]
	v_pk_mul_f32 v[194:195], v[244:245], v[194:195] op_sel:[1,0]
	v_pk_mul_f32 v[196:197], v[244:245], v[196:197] op_sel:[1,0]
	v_pk_mul_f32 v[198:199], v[244:245], v[198:199] op_sel:[1,0]
	v_pk_mul_f32 v[200:201], v[244:245], v[200:201] op_sel:[1,0]
	v_pk_mul_f32 v[202:203], v[244:245], v[202:203] op_sel:[1,0]
	v_pk_fma_f32 v[188:189], v[228:229], v[188:189], v[134:135]
	v_pk_fma_f32 v[190:191], v[230:231], v[190:191], v[136:137]
	v_pk_fma_f32 v[192:193], v[232:233], v[192:193], v[130:131]
	v_pk_fma_f32 v[194:195], v[234:235], v[194:195], v[132:133]
	v_pk_fma_f32 v[196:197], v[236:237], v[196:197], v[142:143]
	v_pk_fma_f32 v[198:199], v[238:239], v[198:199], v[144:145]
	v_pk_fma_f32 v[200:201], v[240:241], v[200:201], v[138:139]
	v_pk_fma_f32 v[202:203], v[242:243], v[202:203], v[140:141]
	global_store_dwordx4 v206, v[188:191], s[12:13]
	global_store_dwordx4 v206, v[192:195], s[12:13] offset:16
	global_store_dwordx4 v206, v[196:199], s[12:13] offset:512
	global_store_dwordx4 v206, v[200:203], s[12:13] offset:528
	s_add_u32 s40, s10, 0x30000
	s_addc_u32 s41, s11, 0
	global_load_dwordx4 v[134:137], v206, s[40:41]
	global_load_dwordx4 v[130:133], v206, s[40:41] offset:16
	global_load_dwordx4 v[142:145], v206, s[40:41] offset:512
	global_load_dwordx4 v[138:141], v206, s[40:41] offset:528
	s_waitcnt vmcnt(12)
; #define ROW_FENCE asm volatile("" ::: "memory")
;     DI void operator()(Acc& acc, const Unit& u, int wr, int wc, int fr, int fq) const {
;     ...
;         for (int aim = 0; aim < 8; ++aim) { const int ai = aim >> 2, m = aim & 3;
;             f32x4 xa[2][2]; f32x2 sv = {0.f, 1.f};
;             if (ln) sv = *(const f32x2*)(st + 2 * (size_t)(row0 + EPI_ROWS(ai, m) + oz_));
; #pragma unroll
;             for (int bj = 0; bj < 2; ++bj) { const float* p = xib + (size_t)(EPI_ROWS(ai, m) + oz_) * D + EPI_COL8(bj); xa[bj][0] = *(const f32x4*)p; xa[bj][1] = *(const f32x4*)(p + 4); }
; #pragma unroll
;             for (int bj = 0; bj < 2; ++bj) { float* p = xob + (size_t)(EPI_ROWS(ai, m) + oz_) * D + EPI_COL8(bj);
;                 *(f32x4*)p = ((xa[bj][0] - sv[0]) * sv[1]) * la[bj][0] + acc[ai][bj][m][0];
;                 *(f32x4*)(p + 4) = ((xa[bj][1] - sv[0]) * sv[1]) * la[bj][1] + acc[ai][bj][m][1]; }
;             if (m & 1) ROW_FENCE;
	v_pk_add_f32 v[64:65], v[64:65], v[246:247] op_sel_hi:[1,0] neg_lo:[0,1] neg_hi:[0,1]
	v_pk_add_f32 v[66:67], v[66:67], v[246:247] op_sel_hi:[1,0] neg_lo:[0,1] neg_hi:[0,1]
	v_pk_add_f32 v[68:69], v[68:69], v[246:247] op_sel_hi:[1,0] neg_lo:[0,1] neg_hi:[0,1]
	v_pk_add_f32 v[70:71], v[70:71], v[246:247] op_sel_hi:[1,0] neg_lo:[0,1] neg_hi:[0,1]
	v_pk_add_f32 v[72:73], v[72:73], v[246:247] op_sel_hi:[1,0] neg_lo:[0,1] neg_hi:[0,1]
	v_pk_add_f32 v[74:75], v[74:75], v[246:247] op_sel_hi:[1,0] neg_lo:[0,1] neg_hi:[0,1]
	v_pk_add_f32 v[76:77], v[76:77], v[246:247] op_sel_hi:[1,0] neg_lo:[0,1] neg_hi:[0,1]
	v_pk_add_f32 v[78:79], v[78:79], v[246:247] op_sel_hi:[1,0] neg_lo:[0,1] neg_hi:[0,1]
	v_pk_mul_f32 v[64:65], v[246:247], v[64:65] op_sel:[1,0]
	v_pk_mul_f32 v[66:67], v[246:247], v[66:67] op_sel:[1,0]
	v_pk_mul_f32 v[68:69], v[246:247], v[68:69] op_sel:[1,0]
	v_pk_mul_f32 v[70:71], v[246:247], v[70:71] op_sel:[1,0]
	v_pk_mul_f32 v[72:73], v[246:247], v[72:73] op_sel:[1,0]
	v_pk_mul_f32 v[74:75], v[246:247], v[74:75] op_sel:[1,0]
	v_pk_mul_f32 v[76:77], v[246:247], v[76:77] op_sel:[1,0]
	v_pk_mul_f32 v[78:79], v[246:247], v[78:79] op_sel:[1,0]
	v_pk_fma_f32 v[64:65], v[228:229], v[64:65], v[118:119]
	v_pk_fma_f32 v[66:67], v[230:231], v[66:67], v[120:121]
	v_pk_fma_f32 v[68:69], v[232:233], v[68:69], v[114:115]
	v_pk_fma_f32 v[70:71], v[234:235], v[70:71], v[116:117]
	v_pk_fma_f32 v[72:73], v[236:237], v[72:73], v[126:127]
	v_pk_fma_f32 v[74:75], v[238:239], v[74:75], v[128:129]
	v_pk_fma_f32 v[76:77], v[240:241], v[76:77], v[122:123]
	v_pk_fma_f32 v[78:79], v[242:243], v[78:79], v[124:125]
	s_add_u32 s14, s12, 0x10000
	s_addc_u32 s15, s13, 0
	global_store_dwordx4 v206, v[64:67], s[14:15]
	global_store_dwordx4 v206, v[68:71], s[14:15] offset:16
	global_store_dwordx4 v206, v[72:75], s[14:15] offset:512
	global_store_dwordx4 v206, v[76:79], s[14:15] offset:528
	s_add_u32 s40, s10, 0x80000
	s_addc_u32 s41, s11, 0
	global_load_dwordx4 v[118:121], v206, s[40:41]
	global_load_dwordx4 v[114:117], v206, s[40:41] offset:16
	global_load_dwordx4 v[126:129], v206, s[40:41] offset:512
	global_load_dwordx4 v[122:125], v206, s[40:41] offset:528
	s_waitcnt vmcnt(16)
	v_pk_add_f32 v[158:159], v[158:159], v[248:249] op_sel_hi:[1,0] neg_lo:[0,1] neg_hi:[0,1]
	v_pk_add_f32 v[160:161], v[160:161], v[248:249] op_sel_hi:[1,0] neg_lo:[0,1] neg_hi:[0,1]
	v_pk_add_f32 v[162:163], v[162:163], v[248:249] op_sel_hi:[1,0] neg_lo:[0,1] neg_hi:[0,1]
	v_pk_add_f32 v[164:165], v[164:165], v[248:249] op_sel_hi:[1,0] neg_lo:[0,1] neg_hi:[0,1]
	v_pk_add_f32 v[166:167], v[166:167], v[248:249] op_sel_hi:[1,0] neg_lo:[0,1] neg_hi:[0,1]
	v_pk_add_f32 v[168:169], v[168:169], v[248:249] op_sel_hi:[1,0] neg_lo:[0,1] neg_hi:[0,1]
	v_pk_add_f32 v[170:171], v[170:171], v[248:249] op_sel_hi:[1,0] neg_lo:[0,1] neg_hi:[0,1]
	v_pk_add_f32 v[172:173], v[172:173], v[248:249] op_sel_hi:[1,0] neg_lo:[0,1] neg_hi:[0,1]
	v_pk_mul_f32 v[158:159], v[248:249], v[158:159] op_sel:[1,0]
	v_pk_mul_f32 v[160:161], v[248:249], v[160:161] op_sel:[1,0]
	v_pk_mul_f32 v[162:163], v[248:249], v[162:163] op_sel:[1,0]
	v_pk_mul_f32 v[164:165], v[248:249], v[164:165] op_sel:[1,0]
	v_pk_mul_f32 v[166:167], v[248:249], v[166:167] op_sel:[1,0]
	v_pk_mul_f32 v[168:169], v[248:249], v[168:169] op_sel:[1,0]
	v_pk_mul_f32 v[170:171], v[248:249], v[170:171] op_sel:[1,0]
	v_pk_mul_f32 v[172:173], v[248:249], v[172:173] op_sel:[1,0]
	v_pk_fma_f32 v[158:159], v[228:229], v[158:159], v[102:103]
	v_pk_fma_f32 v[160:161], v[230:231], v[160:161], v[104:105]
	v_pk_fma_f32 v[162:163], v[232:233], v[162:163], v[98:99]
	v_pk_fma_f32 v[164:165], v[234:235], v[164:165], v[100:101]
	v_pk_fma_f32 v[166:167], v[236:237], v[166:167], v[110:111]
	v_pk_fma_f32 v[168:169], v[238:239], v[168:169], v[112:113]
	v_pk_fma_f32 v[170:171], v[240:241], v[170:171], v[106:107]
	v_pk_fma_f32 v[172:173], v[242:243], v[172:173], v[108:109]
	s_add_u32 s14, s12, 0x20000
	s_addc_u32 s15, s13, 0
	global_store_dwordx4 v206, v[158:161], s[14:15]
	global_store_dwordx4 v206, v[162:165], s[14:15] offset:16
	global_store_dwordx4 v206, v[166:169], s[14:15] offset:512
	global_store_dwordx4 v206, v[170:173], s[14:15] offset:528
	s_add_u32 s40, s10, 0x90000
	s_addc_u32 s41, s11, 0
	global_load_dwordx4 v[102:105], v206, s[40:41]
	global_load_dwordx4 v[98:101], v206, s[40:41] offset:16
	global_load_dwordx4 v[110:113], v206, s[40:41] offset:512
	global_load_dwordx4 v[106:109], v206, s[40:41] offset:528
	s_waitcnt vmcnt(16)
	v_pk_add_f32 v[134:135], v[134:135], v[250:251] op_sel_hi:[1,0] neg_lo:[0,1] neg_hi:[0,1]
	v_pk_add_f32 v[136:137], v[136:137], v[250:251] op_sel_hi:[1,0] neg_lo:[0,1] neg_hi:[0,1]
	v_pk_add_f32 v[130:131], v[130:131], v[250:251] op_sel_hi:[1,0] neg_lo:[0,1] neg_hi:[0,1]
	v_pk_add_f32 v[132:133], v[132:133], v[250:251] op_sel_hi:[1,0] neg_lo:[0,1] neg_hi:[0,1]
	v_pk_add_f32 v[142:143], v[142:143], v[250:251] op_sel_hi:[1,0] neg_lo:[0,1] neg_hi:[0,1]
	v_pk_add_f32 v[144:145], v[144:145], v[250:251] op_sel_hi:[1,0] neg_lo:[0,1] neg_hi:[0,1]
	v_pk_add_f32 v[138:139], v[138:139], v[250:251] op_sel_hi:[1,0] neg_lo:[0,1] neg_hi:[0,1]
	v_pk_add_f32 v[140:141], v[140:141], v[250:251] op_sel_hi:[1,0] neg_lo:[0,1] neg_hi:[0,1]
	v_pk_mul_f32 v[134:135], v[250:251], v[134:135] op_sel:[1,0]
	v_pk_mul_f32 v[136:137], v[250:251], v[136:137] op_sel:[1,0]
	v_pk_mul_f32 v[130:131], v[250:251], v[130:131] op_sel:[1,0]
	v_pk_mul_f32 v[132:133], v[250:251], v[132:133] op_sel:[1,0]
	v_pk_mul_f32 v[142:143], v[250:251], v[142:143] op_sel:[1,0]
	v_pk_mul_f32 v[144:145], v[250:251], v[144:145] op_sel:[1,0]
	v_pk_mul_f32 v[138:139], v[250:251], v[138:139] op_sel:[1,0]
	v_pk_mul_f32 v[140:141], v[250:251], v[140:141] op_sel:[1,0]
	v_pk_fma_f32 v[134:135], v[228:229], v[134:135], v[84:85]
	v_pk_fma_f32 v[136:137], v[230:231], v[136:137], v[86:87]
	v_pk_fma_f32 v[130:131], v[232:233], v[130:131], v[80:81]
	v_pk_fma_f32 v[132:133], v[234:235], v[132:133], v[82:83]
	v_pk_fma_f32 v[142:143], v[236:237], v[142:143], v[92:93]
	v_pk_fma_f32 v[144:145], v[238:239], v[144:145], v[94:95]
	v_pk_fma_f32 v[138:139], v[240:241], v[138:139], v[88:89]
	v_pk_fma_f32 v[140:141], v[242:243], v[140:141], v[90:91]
	s_add_u32 s14, s12, 0x30000
	s_addc_u32 s15, s13, 0
	global_store_dwordx4 v206, v[134:137], s[14:15]
	global_store_dwordx4 v206, v[130:133], s[14:15] offset:16
	global_store_dwordx4 v206, v[142:145], s[14:15] offset:512
	global_store_dwordx4 v206, v[138:141], s[14:15] offset:528
	s_add_u32 s40, s10, 0xa0000
	s_addc_u32 s41, s11, 0
	global_load_dwordx4 v[84:87], v206, s[40:41]
	global_load_dwordx4 v[80:83], v206, s[40:41] offset:16
	global_load_dwordx4 v[92:95], v206, s[40:41] offset:512
	global_load_dwordx4 v[88:91], v206, s[40:41] offset:528
	s_waitcnt vmcnt(16)
; #define ROW_FENCE asm volatile("" ::: "memory")
;     DI void operator()(Acc& acc, const Unit& u, int wr, int wc, int fr, int fq) const {
;     ...
;         for (int aim = 0; aim < 8; ++aim) { const int ai = aim >> 2, m = aim & 3;
;             f32x4 xa[2][2]; f32x2 sv = {0.f, 1.f};
;             if (ln) sv = *(const f32x2*)(st + 2 * (size_t)(row0 + EPI_ROWS(ai, m) + oz_));
; #pragma unroll
;             for (int bj = 0; bj < 2; ++bj) { const float* p = xib + (size_t)(EPI_ROWS(ai, m) + oz_) * D + EPI_COL8(bj); xa[bj][0] = *(const f32x4*)p; xa[bj][1] = *(const f32x4*)(p + 4); }
; #pragma unroll
;             for (int bj = 0; bj < 2; ++bj) { float* p = xob + (size_t)(EPI_ROWS(ai, m) + oz_) * D + EPI_COL8(bj);
;                 *(f32x4*)p = ((xa[bj][0] - sv[0]) * sv[1]) * la[bj][0] + acc[ai][bj][m][0];
;                 *(f32x4*)(p + 4) = ((xa[bj][1] - sv[0]) * sv[1]) * la[bj][1] + acc[ai][bj][m][1]; }
;             if (m & 1) ROW_FENCE;
	v_pk_add_f32 v[118:119], v[118:119], v[252:253] op_sel_hi:[1,0] neg_lo:[0,1] neg_hi:[0,1]
	v_pk_add_f32 v[120:121], v[120:121], v[252:253] op_sel_hi:[1,0] neg_lo:[0,1] neg_hi:[0,1]
	v_pk_add_f32 v[114:115], v[114:115], v[252:253] op_sel_hi:[1,0] neg_lo:[0,1] neg_hi:[0,1]
	v_pk_add_f32 v[116:117], v[116:117], v[252:253] op_sel_hi:[1,0] neg_lo:[0,1] neg_hi:[0,1]
	v_pk_add_f32 v[126:127], v[126:127], v[252:253] op_sel_hi:[1,0] neg_lo:[0,1] neg_hi:[0,1]
	v_pk_add_f32 v[128:129], v[128:129], v[252:253] op_sel_hi:[1,0] neg_lo:[0,1] neg_hi:[0,1]
	v_pk_add_f32 v[122:123], v[122:123], v[252:253] op_sel_hi:[1,0] neg_lo:[0,1] neg_hi:[0,1]
	v_pk_add_f32 v[124:125], v[124:125], v[252:253] op_sel_hi:[1,0] neg_lo:[0,1] neg_hi:[0,1]
	v_pk_mul_f32 v[118:119], v[252:253], v[118:119] op_sel:[1,0]
	v_pk_mul_f32 v[120:121], v[252:253], v[120:121] op_sel:[1,0]
	v_pk_mul_f32 v[114:115], v[252:253], v[114:115] op_sel:[1,0]
	v_pk_mul_f32 v[116:117], v[252:253], v[116:117] op_sel:[1,0]
	v_pk_mul_f32 v[126:127], v[252:253], v[126:127] op_sel:[1,0]
	v_pk_mul_f32 v[128:129], v[252:253], v[128:129] op_sel:[1,0]
	v_pk_mul_f32 v[122:123], v[252:253], v[122:123] op_sel:[1,0]
	v_pk_mul_f32 v[124:125], v[252:253], v[124:125] op_sel:[1,0]
	v_pk_fma_f32 v[118:119], v[228:229], v[118:119], v[52:53]
	v_pk_fma_f32 v[120:121], v[230:231], v[120:121], v[54:55]
	v_pk_fma_f32 v[114:115], v[232:233], v[114:115], v[48:49]
	v_pk_fma_f32 v[116:117], v[234:235], v[116:117], v[50:51]
	v_pk_fma_f32 v[126:127], v[236:237], v[126:127], v[60:61]
	v_pk_fma_f32 v[128:129], v[238:239], v[128:129], v[62:63]
	v_pk_fma_f32 v[122:123], v[240:241], v[122:123], v[56:57]
	v_pk_fma_f32 v[124:125], v[242:243], v[124:125], v[58:59]
	s_add_u32 s14, s12, 0x80000
	s_addc_u32 s15, s13, 0
	global_store_dwordx4 v206, v[118:121], s[14:15]
	global_store_dwordx4 v206, v[114:117], s[14:15] offset:16
	global_store_dwordx4 v206, v[126:129], s[14:15] offset:512
	global_store_dwordx4 v206, v[122:125], s[14:15] offset:528
	s_add_u32 s40, s10, 0xb0000
	s_addc_u32 s41, s11, 0
	global_load_dwordx4 v[52:55], v206, s[40:41]
	global_load_dwordx4 v[48:51], v206, s[40:41] offset:16
	global_load_dwordx4 v[60:63], v206, s[40:41] offset:512
	global_load_dwordx4 v[56:59], v206, s[40:41] offset:528
	s_waitcnt vmcnt(16)
	v_pk_add_f32 v[102:103], v[102:103], v[174:175] op_sel_hi:[1,0] neg_lo:[0,1] neg_hi:[0,1]
	v_pk_add_f32 v[104:105], v[104:105], v[174:175] op_sel_hi:[1,0] neg_lo:[0,1] neg_hi:[0,1]
	v_pk_add_f32 v[98:99], v[98:99], v[174:175] op_sel_hi:[1,0] neg_lo:[0,1] neg_hi:[0,1]
	v_pk_add_f32 v[100:101], v[100:101], v[174:175] op_sel_hi:[1,0] neg_lo:[0,1] neg_hi:[0,1]
	v_pk_add_f32 v[110:111], v[110:111], v[174:175] op_sel_hi:[1,0] neg_lo:[0,1] neg_hi:[0,1]
	v_pk_add_f32 v[112:113], v[112:113], v[174:175] op_sel_hi:[1,0] neg_lo:[0,1] neg_hi:[0,1]
	v_pk_add_f32 v[106:107], v[106:107], v[174:175] op_sel_hi:[1,0] neg_lo:[0,1] neg_hi:[0,1]
	v_pk_add_f32 v[108:109], v[108:109], v[174:175] op_sel_hi:[1,0] neg_lo:[0,1] neg_hi:[0,1]
	v_pk_mul_f32 v[102:103], v[174:175], v[102:103] op_sel:[1,0]
	v_pk_mul_f32 v[104:105], v[174:175], v[104:105] op_sel:[1,0]
	v_pk_mul_f32 v[98:99], v[174:175], v[98:99] op_sel:[1,0]
	v_pk_mul_f32 v[100:101], v[174:175], v[100:101] op_sel:[1,0]
	v_pk_mul_f32 v[110:111], v[174:175], v[110:111] op_sel:[1,0]
	v_pk_mul_f32 v[112:113], v[174:175], v[112:113] op_sel:[1,0]
	v_pk_mul_f32 v[106:107], v[174:175], v[106:107] op_sel:[1,0]
	v_pk_mul_f32 v[108:109], v[174:175], v[108:109] op_sel:[1,0]
	v_pk_fma_f32 v[102:103], v[228:229], v[102:103], v[36:37]
	v_pk_fma_f32 v[104:105], v[230:231], v[104:105], v[38:39]
	v_pk_fma_f32 v[98:99], v[232:233], v[98:99], v[32:33]
	v_pk_fma_f32 v[100:101], v[234:235], v[100:101], v[34:35]
	v_pk_fma_f32 v[110:111], v[236:237], v[110:111], v[44:45]
	v_pk_fma_f32 v[112:113], v[238:239], v[112:113], v[46:47]
	v_pk_fma_f32 v[106:107], v[240:241], v[106:107], v[40:41]
	v_pk_fma_f32 v[108:109], v[242:243], v[108:109], v[42:43]
	s_add_u32 s14, s12, 0x90000
	s_addc_u32 s15, s13, 0
	global_store_dwordx4 v206, v[102:105], s[14:15]
	global_store_dwordx4 v206, v[98:101], s[14:15] offset:16
	global_store_dwordx4 v206, v[110:113], s[14:15] offset:512
	global_store_dwordx4 v206, v[106:109], s[14:15] offset:528
	s_waitcnt vmcnt(12)
; #define PG8_BAR __builtin_amdgcn_s_barrier()
; #define ROW_FENCE asm volatile("" ::: "memory")
;     ...
;         cur = nxt; cA = nA; cB = nB; ++ui;
;         if (wr == 1) PG8_BAR;
;     DI void operator()(Acc& acc, const Unit& u, int wr, int wc, int fr, int fq) const {
;     ...
;         for (int aim = 0; aim < 8; ++aim) { const int ai = aim >> 2, m = aim & 3;
;             f32x4 xa[2][2]; f32x2 sv = {0.f, 1.f};
;             if (ln) sv = *(const f32x2*)(st + 2 * (size_t)(row0 + EPI_ROWS(ai, m) + oz_));
; #pragma unroll
;             for (int bj = 0; bj < 2; ++bj) { const float* p = xib + (size_t)(EPI_ROWS(ai, m) + oz_) * D + EPI_COL8(bj); xa[bj][0] = *(const f32x4*)p; xa[bj][1] = *(const f32x4*)(p + 4); }
; #pragma unroll
;             for (int bj = 0; bj < 2; ++bj) { float* p = xob + (size_t)(EPI_ROWS(ai, m) + oz_) * D + EPI_COL8(bj);
;                 *(f32x4*)p = ((xa[bj][0] - sv[0]) * sv[1]) * la[bj][0] + acc[ai][bj][m][0];
;                 *(f32x4*)(p + 4) = ((xa[bj][1] - sv[0]) * sv[1]) * la[bj][1] + acc[ai][bj][m][1]; }
;             if (m & 1) ROW_FENCE;
	v_pk_add_f32 v[84:85], v[84:85], v[176:177] op_sel_hi:[1,0] neg_lo:[0,1] neg_hi:[0,1]
	v_pk_add_f32 v[86:87], v[86:87], v[176:177] op_sel_hi:[1,0] neg_lo:[0,1] neg_hi:[0,1]
	v_pk_add_f32 v[80:81], v[80:81], v[176:177] op_sel_hi:[1,0] neg_lo:[0,1] neg_hi:[0,1]
	v_pk_add_f32 v[82:83], v[82:83], v[176:177] op_sel_hi:[1,0] neg_lo:[0,1] neg_hi:[0,1]
	v_pk_add_f32 v[92:93], v[92:93], v[176:177] op_sel_hi:[1,0] neg_lo:[0,1] neg_hi:[0,1]
	v_pk_add_f32 v[94:95], v[94:95], v[176:177] op_sel_hi:[1,0] neg_lo:[0,1] neg_hi:[0,1]
	v_pk_add_f32 v[88:89], v[88:89], v[176:177] op_sel_hi:[1,0] neg_lo:[0,1] neg_hi:[0,1]
	v_pk_add_f32 v[90:91], v[90:91], v[176:177] op_sel_hi:[1,0] neg_lo:[0,1] neg_hi:[0,1]
	v_pk_mul_f32 v[84:85], v[176:177], v[84:85] op_sel:[1,0]
	v_pk_mul_f32 v[86:87], v[176:177], v[86:87] op_sel:[1,0]
	v_pk_mul_f32 v[80:81], v[176:177], v[80:81] op_sel:[1,0]
	v_pk_mul_f32 v[82:83], v[176:177], v[82:83] op_sel:[1,0]
	v_pk_mul_f32 v[92:93], v[176:177], v[92:93] op_sel:[1,0]
	v_pk_mul_f32 v[94:95], v[176:177], v[94:95] op_sel:[1,0]
	v_pk_mul_f32 v[88:89], v[176:177], v[88:89] op_sel:[1,0]
	v_pk_mul_f32 v[90:91], v[176:177], v[90:91] op_sel:[1,0]
	v_pk_fma_f32 v[84:85], v[228:229], v[84:85], v[20:21]
	v_pk_fma_f32 v[86:87], v[230:231], v[86:87], v[22:23]
	v_pk_fma_f32 v[80:81], v[232:233], v[80:81], v[16:17]
	v_pk_fma_f32 v[82:83], v[234:235], v[82:83], v[18:19]
	v_pk_fma_f32 v[92:93], v[236:237], v[92:93], v[28:29]
	v_pk_fma_f32 v[94:95], v[238:239], v[94:95], v[30:31]
	v_pk_fma_f32 v[88:89], v[240:241], v[88:89], v[24:25]
	v_pk_fma_f32 v[90:91], v[242:243], v[90:91], v[26:27]
	s_add_u32 s14, s12, 0xa0000
	s_addc_u32 s15, s13, 0
	global_store_dwordx4 v206, v[84:87], s[14:15]
	global_store_dwordx4 v206, v[80:83], s[14:15] offset:16
	global_store_dwordx4 v206, v[92:95], s[14:15] offset:512
	global_store_dwordx4 v206, v[88:91], s[14:15] offset:528
	s_waitcnt vmcnt(8)
	v_pk_add_f32 v[52:53], v[52:53], v[204:205] op_sel_hi:[1,0] neg_lo:[0,1] neg_hi:[0,1]
	v_pk_add_f32 v[54:55], v[54:55], v[204:205] op_sel_hi:[1,0] neg_lo:[0,1] neg_hi:[0,1]
	v_pk_add_f32 v[48:49], v[48:49], v[204:205] op_sel_hi:[1,0] neg_lo:[0,1] neg_hi:[0,1]
	v_pk_add_f32 v[50:51], v[50:51], v[204:205] op_sel_hi:[1,0] neg_lo:[0,1] neg_hi:[0,1]
	v_pk_add_f32 v[60:61], v[60:61], v[204:205] op_sel_hi:[1,0] neg_lo:[0,1] neg_hi:[0,1]
	v_pk_add_f32 v[62:63], v[62:63], v[204:205] op_sel_hi:[1,0] neg_lo:[0,1] neg_hi:[0,1]
	v_pk_add_f32 v[56:57], v[56:57], v[204:205] op_sel_hi:[1,0] neg_lo:[0,1] neg_hi:[0,1]
	v_pk_add_f32 v[58:59], v[58:59], v[204:205] op_sel_hi:[1,0] neg_lo:[0,1] neg_hi:[0,1]
	v_pk_mul_f32 v[52:53], v[204:205], v[52:53] op_sel:[1,0]
	v_pk_mul_f32 v[54:55], v[204:205], v[54:55] op_sel:[1,0]
	v_pk_mul_f32 v[48:49], v[204:205], v[48:49] op_sel:[1,0]
	v_pk_mul_f32 v[50:51], v[204:205], v[50:51] op_sel:[1,0]
	v_pk_mul_f32 v[60:61], v[204:205], v[60:61] op_sel:[1,0]
	v_pk_mul_f32 v[62:63], v[204:205], v[62:63] op_sel:[1,0]
	v_pk_mul_f32 v[56:57], v[204:205], v[56:57] op_sel:[1,0]
	v_pk_mul_f32 v[58:59], v[204:205], v[58:59] op_sel:[1,0]
	v_pk_fma_f32 v[52:53], v[228:229], v[52:53], v[8:9]
	v_pk_fma_f32 v[54:55], v[230:231], v[54:55], v[10:11]
	v_pk_fma_f32 v[48:49], v[232:233], v[48:49], v[4:5]
	v_pk_fma_f32 v[50:51], v[234:235], v[50:51], v[6:7]
	v_pk_fma_f32 v[60:61], v[236:237], v[60:61], v[12:13]
	v_pk_fma_f32 v[62:63], v[238:239], v[62:63], v[14:15]
	v_pk_fma_f32 v[56:57], v[240:241], v[56:57], v[0:1]
	v_pk_fma_f32 v[58:59], v[242:243], v[58:59], v[2:3]
	s_add_u32 s14, s12, 0xb0000
	s_addc_u32 s15, s13, 0
	global_store_dwordx4 v206, v[52:55], s[14:15]
	global_store_dwordx4 v206, v[48:51], s[14:15] offset:16
	global_store_dwordx4 v206, v[60:63], s[14:15] offset:512
	global_store_dwordx4 v206, v[56:59], s[14:15] offset:528
	s_mov_b64 s[4:5], -1
	s_andn2_b64 vcc, exec, s[2:3]
	s_cbranch_vccnz .LBB0_133
	v_readlane_b32 s2, v255, 51
	v_readlane_b32 s3, v255, 52
	s_andn2_b64 vcc, exec, s[2:3]
	s_cbranch_vccnz .LBB0_132
	s_barrier
	s_branch .LBB0_132
